# k40 + modulation GEMM touches each 512 KB weight tile up front (8 dword loads per lane) so the cold misses overlap instead of serialising the K loop
# baseline (speedup 1.0000x reference)
; #define PG8_STAGE(bufoff, gbase, voff) do { _Pragma("unroll") for (int _i = 0; _i < 2; ++_i) \
;         __builtin_amdgcn_global_load_lds((const unsigned*)((const char*)(gbase) + (voff)[_i]), (LAS unsigned*)(lds + (bufoff) + ldsw + _i * 8192), 16, 0, 0); } while (0)
; #define PG8_WAIT_V(n) asm volatile("s_waitcnt vmcnt(" #n ")" ::: "memory")
; #define PG8_BAR __builtin_amdgcn_s_barrier()
; template <class Epi, bool ALIGN_EPI>
; __device__ __forceinline__ void gemm_phase(LAS unsigned char* lds, const Gemm g, const Order& S, const Epi& E, const int wave_id) {
;     ...
;     for (int i = 0; i < 2; ++i) { int R, C; stage_rc(tid * 16 + i * 8192, R, C); const int Rb = Epi::PERM ? ((R & ~31) + perm32(R & 31)) : R; voffA[i] = (unsigned)(R * g.lda + C) * 2u; voffB[i] = (unsigned)(Rb * g.ldb + C) * 2u; }
;     const size_t kstep = (size_t)(BK * 2);
;     const size_t hstepA = (size_t)HALF * g.lda * 2, hstepB = (size_t)HALF * g.ldb * 2;
;     const unsigned ldsw = (unsigned)wid * 1024u;
;     const int aoff = lds_byte(wr * 64 + fr, fq * 8), boff = lds_byte(wc * 32 + fr, fq * 8);
;     ...
;     Unit cur, nxt; int ui = 0;
;     if (!S.next(0, cur)) return;
;     f32x4 acc[2][2][4][2];
; #pragma unroll
;     for (int a = 0; a < 2; ++a)
; #pragma unroll
;         for (int b = 0; b < 2; ++b)
; #pragma unroll
;             for (int m = 0; m < 4; ++m)
; #pragma unroll
;                 for (int n = 0; n < 2; ++n) acc[a][b][m][n] = (f32x4){0.f, 0.f, 0.f, 0.f};
;     bf16x8 At[4][2], B0[2][2], B1[2][2];
;     const char* cA = (const char*)g.A + (size_t)cur.z * g.sAz + (size_t)cur.pm * 2 * hstepA + (size_t)cur.k0 * 2; const char* cB = (const char*)g.Bt + (size_t)cur.z * g.sBz + (size_t)cur.pn * 2 * hstepB + (size_t)cur.k0 * 2;
;     PG8_STAGE(PG8_SB(0, 0), cB, voffB); PG8_STAGE(PG8_SB(0, 1), cB + hstepB, voffB); PG8_STAGE(PG8_SA(0, 0), cA, voffA); PG8_STAGE(PG8_SA(0, 1), cA + hstepA, voffA);
;     if (wr == 1) PG8_BAR;
;     PG8_WAIT_V(2); PG8_BAR;
;     PG8_STAGE(PG8_SB(1, 0), cB + kstep, voffB); PG8_STAGE(PG8_SA(1, 0), cA + kstep, voffA); PG8_STAGE(PG8_SB(1, 1), cB + hstepB + kstep, voffB);
;     PG8_WAIT_V(6); PG8_BAR;
.LBB0_213:
	s_add_u32 s4, s6, 0x300000
	s_addc_u32 s5, s7, 0
	s_add_u32 s33, s6, 0xe100000
	s_addc_u32 s34, s7, 0
	s_lshl_b32 s35, s26, 10
	v_lshl_add_u32 v0, v4, 4, s35
	v_ashrrev_i32_e32 v1, 31, v0
	v_lshrrev_b32_e32 v1, 22, v1
	v_add_u32_e32 v1, v0, v1
	v_ashrrev_i32_e32 v5, 10, v1
	v_mul_i32_i24_e32 v1, 0x400, v5
	v_sub_u32_e32 v1, v0, v1
	v_lshrrev_b32_e32 v2, 4, v1
	v_bitop3_b32 v1, v2, v1, 32 bitop3:0x6c
	v_ashrrev_i32_e32 v3, 31, v1
	v_lshrrev_b32_e32 v3, 26, v3
	v_add_u32_e32 v3, v1, v3
	v_ashrrev_i32_e32 v6, 6, v3
	v_and_b32_e32 v3, 0xc0, v3
	v_sub_u32_e32 v1, v1, v3
	v_mov_b32_e32 v3, 1
	v_lshlrev_b32_e32 v2, 3, v5
	v_lshlrev_b32_e32 v7, 5, v5
	v_ashrrev_i16_sdwa v1, v3, sext(v1) dst_sel:DWORD dst_unused:UNUSED_PAD src0_sel:DWORD src1_sel:BYTE_0
	v_and_b32_e32 v2, 0x1ffff0, v2
	v_and_b32_e32 v7, 32, v7
	v_bfe_i32 v8, v1, 0, 16
	v_add_u32_e32 v1, v7, v8
	v_add_lshl_u32 v2, v6, v2, 11
	v_add_u32_e32 v0, 0x2000, v0
	v_lshl_add_u32 v128, v1, 1, v2
	v_ashrrev_i32_e32 v1, 31, v0
	v_lshrrev_b32_e32 v1, 22, v1
	v_add_u32_e32 v1, v0, v1
	v_ashrrev_i32_e32 v7, 10, v1
	v_mul_i32_i24_e32 v1, 0x400, v7
	v_sub_u32_e32 v0, v0, v1
	v_lshrrev_b32_e32 v1, 4, v0
	v_bitop3_b32 v0, v1, v0, 32 bitop3:0x6c
	v_ashrrev_i32_e32 v2, 31, v0
	v_lshrrev_b32_e32 v2, 26, v2
	v_add_u32_e32 v2, v0, v2
	v_ashrrev_i32_e32 v9, 6, v2
	v_and_b32_e32 v2, 0xffc0, v2
	s_ashr_i32 s0, s26, 2
	s_mul_i32 s2, s51, 0xc00000
	v_sub_u32_e32 v0, v0, v2
	s_mul_hi_i32 s1, s51, 0xc00000
	s_add_u32 s8, s33, s2
	v_lshrrev_b16_e32 v2, 7, v0
	s_addc_u32 s1, s34, s1
	s_ashr_i32 s19, s18, 31
	v_and_b32_e32 v2, 1, v2
	s_lshl_b64 s[2:3], s[18:19], 19
	v_add_u16_e32 v0, v0, v2
	s_add_u32 s20, s8, s2
	v_lshlrev_b32_e32 v1, 3, v7
	v_lshlrev_b32_e32 v10, 5, v7
	v_ashrrev_i16_sdwa v0, v3, sext(v0) dst_sel:DWORD dst_unused:UNUSED_PAD src0_sel:DWORD src1_sel:BYTE_0
	s_addc_u32 s21, s1, s3
	s_add_i32 s36, s35, 0
	v_and_b32_e32 v1, 0x1ffff0, v1
	v_and_b32_e32 v11, 32, v10
	v_bfe_i32 v10, v0, 0, 16
	s_add_i32 m0, s36, 0x10000
	v_add_u32_e32 v0, v11, v10
	v_add_lshl_u32 v1, v9, v1, 11
	global_load_lds_dwordx4 v128, s[20:21]
	s_add_i32 m0, s36, 0x12000
	v_lshl_add_u32 v130, v0, 1, v1
	s_add_u32 s2, s20, 0x40000
	global_load_lds_dwordx4 v130, s[20:21]
	s_addc_u32 s3, s21, 0
	s_add_i32 m0, s36, 0x14000
	s_add_i32 s37, s36, 0x2000
	global_load_lds_dwordx4 v128, s[2:3]
	s_add_i32 m0, s36, 0x16000
	v_mov_b32_e32 v129, 0
	global_load_lds_dwordx4 v130, s[2:3]
	s_mov_b32 m0, s36
	s_add_u32 s2, s6, 0x340000
	global_load_lds_dwordx4 v128, s[4:5]
	s_mov_b32 m0, s37
	s_addc_u32 s3, s7, 0
	s_add_i32 s38, s36, 0x4000
	global_load_lds_dwordx4 v130, s[4:5]
	s_mov_b32 m0, s38
	s_add_i32 s39, s36, 0x6000
	global_load_lds_dwordx4 v128, s[2:3]
	s_mov_b32 m0, s39
	v_mov_b32_e32 v131, v129
	global_load_lds_dwordx4 v130, s[2:3]
	v_lshlrev_b32_e32 v249, 7, v144
	global_load_dword v250, v249, s[20:21]
	v_add_u32_e32 v249, 0x10000, v249
	global_load_dword v250, v249, s[20:21]
	v_add_u32_e32 v249, 0x10000, v249
	global_load_dword v250, v249, s[20:21]
	v_add_u32_e32 v249, 0x10000, v249
	global_load_dword v250, v249, s[20:21]
	v_add_u32_e32 v249, 0x10000, v249
	global_load_dword v250, v249, s[20:21]
	v_add_u32_e32 v249, 0x10000, v249
	global_load_dword v250, v249, s[20:21]
	v_add_u32_e32 v249, 0x10000, v249
	global_load_dword v250, v249, s[20:21]
	v_add_u32_e32 v249, 0x10000, v249
	global_load_dword v250, v249, s[20:21]
	s_cmp_eq_u32 s0, 1
	s_mov_b32 s40, 0
	v_lshl_add_u64 v[2:3], s[20:21], 0, v[128:129]
	v_lshl_add_u64 v[0:1], s[20:21], 0, v[130:131]
	s_cselect_b64 s[8:9], -1, 0
	s_cmp_lg_u32 s0, 1
	s_movk_i32 s41, 0x6000
	s_cbranch_scc1 .LBB0_215
	s_barrier

;     __device__ __forceinline__ void operator()(const Acc& acc, const Unit& u, int wr, int wc, int fr, int fq) const {
; #pragma unroll
;         for (int ai = 0; ai < 2; ++ai)
; #pragma unroll
;             for (int m = 0; m < 4; ++m) { const int row = ai * 128 + wr * 64 + m * 16 + fr;
;                 if (row < NMODROWS) {
; #pragma unroll
;                     for (int bj = 0; bj < 2; ++bj)
; #pragma unroll
;                         for (int n = 0; n < 2; ++n) { const int col = u.pn * 256 + bj * 128 + wc * 32 + n * 16 + fq * 4;
;                             const f32x4 b = *(const f32x4*)(bmod + (size_t)u.z * 6144 + col);
;                             *(f32x4*)(mod + ((size_t)u.z * NMODROWS + row) * 6144 + col) = acc[ai][bj][m][n] + b; } } }
.LBB0_230:
	v_mov_b32_e32 v140, v145
	v_mov_b32_e32 v141, v146
	s_lshl_b32 s17, s18, 8
	s_or_b32 s17, s17, s43
	v_add_u32_e32 v142, s42, v140
	v_lshl_add_u32 v140, v141, 2, s17
	s_mul_hi_i32 s17, s51, 0x6000
	s_mul_i32 s22, s51, 0x6000
	s_mul_hi_i32 s19, s51, 0x84
	s_mul_i32 s18, s51, 0x84
	v_ashrrev_i32_e32 v141, 31, v140
	s_add_u32 s20, s31, s22
	s_addc_u32 s21, s30, s17
	v_lshlrev_b64 v[180:181], 2, v[140:141]
	v_lshl_add_u64 v[180:181], s[20:21], 0, v[180:181]
	global_load_dwordx4 v[164:167], v[180:181], off
	global_load_dwordx4 v[168:171], v[180:181], off offset:64
	global_load_dwordx4 v[172:175], v[180:181], off offset:512
	global_load_dwordx4 v[176:179], v[180:181], off offset:576
	v_cmp_gt_i32_e32 vcc, s49, v142
	s_waitcnt vmcnt(0)
	v_lshlrev_b32_e32 v249, 7, v144
	global_load_dword v250, v249, s[2:3]
	v_add_u32_e32 v249, 0x10000, v249
	global_load_dword v250, v249, s[2:3]
	v_add_u32_e32 v249, 0x10000, v249
	global_load_dword v250, v249, s[2:3]
	v_add_u32_e32 v249, 0x10000, v249
	global_load_dword v250, v249, s[2:3]
	v_add_u32_e32 v249, 0x10000, v249
	global_load_dword v250, v249, s[2:3]
	v_add_u32_e32 v249, 0x10000, v249
	global_load_dword v250, v249, s[2:3]
	v_add_u32_e32 v249, 0x10000, v249
	global_load_dword v250, v249, s[2:3]
	v_add_u32_e32 v249, 0x10000, v249
	global_load_dword v250, v249, s[2:3]
	s_and_saveexec_b64 s[20:21], vcc
	s_cbranch_execz .LBB0_232
	v_lshlrev_b64 v[156:157], 2, v[140:141]
	v_ashrrev_i32_e32 v143, 31, v142
	v_mov_b64_e32 v[160:161], s[10:11]
	v_lshl_add_u64 v[162:163], s[18:19], 0, v[142:143]
	v_mad_u64_u32 v[160:161], s[24:25], v162, s41, v[160:161]
	v_mov_b32_e32 v162, v161
	v_mad_u64_u32 v[162:163], s[24:25], v163, s41, v[162:163]
	v_mov_b32_e32 v161, v162
	v_lshl_add_u64 v[156:157], v[160:161], 0, v[156:157]
	v_pk_add_f32 v[126:127], v[126:127], v[166:167]
	v_pk_add_f32 v[124:125], v[124:125], v[164:165]
	global_store_dwordx4 v[156:157], v[124:127], off
	v_pk_add_f32 v[122:123], v[122:123], v[170:171]
	v_pk_add_f32 v[120:121], v[120:121], v[168:169]
	global_store_dwordx4 v[156:157], v[120:123], off offset:64
	v_pk_add_f32 v[118:119], v[118:119], v[174:175]
	v_pk_add_f32 v[116:117], v[116:117], v[172:173]
	global_store_dwordx4 v[156:157], v[116:119], off offset:512
	v_pk_add_f32 v[114:115], v[114:115], v[178:179]
	v_pk_add_f32 v[112:113], v[112:113], v[176:177]
	global_store_dwordx4 v[156:157], v[112:115], off offset:576
